# dn_scan: per-step barrier 1 removed (tile/U/g/state reads all complete before barrier 3), OUT flush moved behind barrier 2
# speedup vs baseline: 1.0063x; 1.0063x over previous
.LBB0_1377:
	s_or_b64 exec, exec, s[10:11]
	s_and_b64 s[8:9], s[2:3], exec
	s_cselect_b32 s9, s60, s62
	v_readlane_b32 s10, v254, 23
	s_cselect_b32 s8, s61, s63
	v_and_b32_e32 v50, 15, v39
	v_lshrrev_b32_e32 v52, 2, v39
	v_readlane_b32 s11, v254, 24
	s_add_u32 s9, s9, s10
	v_bfe_u32 v37, v39, 4, 2
	v_mul_u32_u24_e32 v51, 0x48, v50
	v_and_b32_e32 v52, 48, v52
	s_addc_u32 s10, s8, 0
	s_lshl_b32 s11, s19, 5
	v_lshl_add_u32 v51, v51, 1, s33
	v_lshlrev_b32_e32 v53, 1, v52
	v_lshlrev_b32_e32 v54, 2, v37
	v_lshlrev_b32_e32 v55, 3, v37
	v_lshlrev_b32_e32 v37, 4, v37
	s_add_u32 s8, s9, s11
	v_add3_u32 v86, v51, v53, v55
	v_or_b32_e32 v53, v52, v50
	v_add_u32_e32 v83, v51, v37
	s_addc_u32 s9, s10, 0
	v_lshlrev_b32_e32 v50, 1, v50
	v_mov_b32_e32 v51, v129
	v_lshl_add_u64 v[60:61], s[8:9], 0, v[50:51]
	v_and_b32_e32 v104, 0xff, v131
	v_lshrrev_b32_e32 v104, 1, v104
	v_lshlrev_b32_e32 v104, 9, v104
	v_and_b32_e32 v105, 1, v131
	v_lshl_or_b32 v104, v105, 4, v104
	v_mov_b32_e32 v105, 0
	v_lshl_add_u64 v[104:105], s[8:9], 0, v[104:105]
	v_lshrrev_b32_e32 v51, 1, v42
	v_mul_u32_u24_e32 v51, 48, v51
	v_lshl_add_u32 v49, v49, 1, s33
	v_add3_u32 v96, s33, v51, v36
	v_mul_u32_u24_e32 v36, 0x48, v44
	v_lshl_add_u32 v100, v36, 1, v49
	v_mul_u32_u24_e32 v36, 0x48, v45
	v_lshlrev_b32_e32 v36, 1, v36
	v_lshlrev_b32_e32 v43, 1, v43
	v_mul_u32_u24_e32 v53, 0x48, v53
	v_add3_u32 v99, s33, v36, v43
	v_mul_u32_u24_e32 v36, 0x48, v46
	v_lshlrev_b32_e32 v53, 1, v53
	v_lshl_add_u32 v98, v36, 1, v49
	v_mul_u32_u24_e32 v36, 0x48, v48
	v_add3_u32 v82, s33, v53, v37
	v_or_b32_e32 v37, v54, v52
	v_lshlrev_b32_e32 v36, 1, v36
	v_bitop3_b32 v48, v54, 63, v52 bitop3:0x36
	v_lshl_add_u32 v84, v37, 2, s33
	v_add3_u32 v97, s33, v36, v43
	v_mad_u32_u24 v43, v37, 48, s33
	v_or_b32_e32 v36, 1, v37
	v_mul_i32_i24_e32 v44, 0xffffffd4, v37
	v_or_b32_e32 v45, 2, v37
	v_or_b32_e32 v46, 3, v37
	v_cndmask_b32_e64 v85, v48, v37, s[2:3]
	v_bitop3_b32 v37, v54, 62, v52 bitop3:0x36
	v_cndmask_b32_e64 v81, v37, v36, s[2:3]
	v_bitop3_b32 v36, v54, 61, v52 bitop3:0x36
	v_cndmask_b32_e64 v80, v36, v45, s[2:3]
	v_bitop3_b32 v36, v54, 60, v52 bitop3:0x36
	v_cndmask_b32_e64 v78, v36, v46, s[2:3]
	v_and_b32_e32 v36, 0x1f80, v47
	v_and_b32_e32 v37, 1, v39
	v_or_b32_e32 v36, s13, v36
	v_lshlrev_b32_e32 v37, 4, v37
	v_readlane_b32 s8, v254, 11
	v_or3_b32 v36, v36, s11, v37
	v_mov_b32_e32 v37, s17
	v_readlane_b32 s9, v254, 12
	v_mov_b32_e32 v39, v129
	v_add_u32_e32 v95, s33, v38
	v_lshl_add_u64 v[70:71], s[8:9], 0, v[36:37]
	v_readlane_b32 s8, v254, 13
	v_add_u32_e32 v93, v43, v50
	v_lshl_add_u64 v[38:39], v[40:41], 0, v[38:39]
	v_readlane_b32 s9, v254, 14
	v_lshl_or_b32 v36, v42, 4, s13
	s_lshl_b32 s16, s16, 12
	v_add_u32_e32 v92, 48, v93
	v_add_u32_e32 v89, 0x60, v93
	v_add_u32_e32 v87, 0x90, v93
	v_lshl_add_u64 v[72:73], s[8:9], 0, v[38:39]
	v_lshl_add_u64 v[74:75], s[52:53], 0, v[36:37]
	v_lshl_add_u64 v[76:77], s[56:57], 0, v[36:37]
	s_movk_i32 s17, 0x42
	s_mov_b32 s19, -3
	s_mov_b64 s[8:9], 0
	v_add_u32_e32 v79, v43, v44
	v_mov_b32_e32 v67, v66
	v_mov_b32_e32 v68, v66
	v_mov_b32_e32 v69, v66
	v_and_b32_e32 v204, 15, v131
	v_lshlrev_b32_e32 v204, 1, v204
	v_add_u32_e32 v204, 0xc000, v204
	v_add_u32_e32 v204, s33, v204
	v_lshl_add_u32 v107, v85, 5, v204
	v_lshl_add_u32 v112, v81, 5, v204
	v_lshl_add_u32 v133, v80, 5, v204
	v_lshl_add_u32 v188, v78, 5, v204
	v_and_b32_e32 v204, 0xff, v131
	v_lshlrev_b32_e32 v204, 4, v204
	v_add_u32_e32 v204, 0xc000, v204
	v_add_u32_e32 v204, s33, v204
	v_readfirstlane_b32 s25, v131
	s_nop 0
	s_lshr_b32 s25, s25, 8
	s_and_b32 s25, s25, 1
	s_lshl_b32 s26, s25, 16
	s_nop 0
	v_subrev_u32_e32 v82, s26, v82
	v_subrev_u32_e32 v97, s26, v97
	v_subrev_u32_e32 v98, s26, v98
	v_subrev_u32_e32 v99, s26, v99
	v_subrev_u32_e32 v100, s26, v100
	s_barrier
.LBB0_1378:
	s_waitcnt vmcnt(0)
	s_cmp_eq_u32 s25, 0
	s_cbranch_scc0 .Lscan_st1
	ds_write_b128 v100, v[4:7]
	ds_write_b128 v100, v[8:11] offset:9216
	ds_write_b128 v98, v[16:19]
	ds_write_b128 v98, v[20:23] offset:9216
	s_branch .Lscan_std

.Lscan_std:
	s_and_saveexec_b64 s[10:11], s[4:5]
	ds_write_b128 v96, v[0:3] offset:36864
	s_or_b64 exec, exec, s[10:11]
	s_and_saveexec_b64 s[10:11], s[6:7]
	ds_write_b32 v95, v94 offset:46848
	s_or_b64 exec, exec, s[10:11]
	v_cvt_pk_bf16_f32 v4, v66, v67
	v_cvt_pk_bf16_f32 v5, v68, v69
	ds_write_b64 v86, v[4:5] offset:39936
	s_waitcnt lgkmcnt(0)
	s_barrier
	s_cmp_gt_i32 s19, -3
	s_cbranch_scc0 .Lscan_nofl
	s_and_saveexec_b64 s[10:11], s[4:5]
	ds_read_b128 v[240:243], v204
	s_lshl_b32 s26, s24, 9
	s_mov_b32 s27, 0
	v_lshl_add_u64 v[150:151], v[104:105], 0, s[26:27]
	s_waitcnt lgkmcnt(0)
	global_store_dwordx4 v[150:151], v[240:243], off
	s_or_b64 exec, exec, s[10:11]
.Lscan_nofl:
	v_mov_b32_e32 v102, s33
	v_add_u32_e32 v65, 0xb704, v79
	ds_read_b128 v[36:39], v82
	ds_read_b128 v[40:43], v83 offset:39936
	ds_read_b128 v[44:47], v82 offset:64
	ds_read_b128 v[48:51], v83 offset:40000
	ds_read_b32 v101, v102 offset:47100
	ds_read_b32 v208, v84 offset:46848
	ds_read2_b32 v[210:211], v65 offset1:1
	ds_read_b32 v209, v79 offset:46860
	ds_read_u16 v212, v93 offset:36864
	ds_read_u16 v213, v92 offset:36864
	ds_read_u16 v214, v89 offset:36864
	ds_read_u16 v215, v87 offset:36864
	s_cmp_gt_i32 s19, 63
	s_cbranch_scc1 .Lscan_skip
	s_add_i32 s10, s19, 3
	s_cmp_gt_u32 s10, 2
	s_mov_b64 s[10:11], -1
	s_cbranch_scc0 .LBB0_1384
	s_and_b64 s[10:11], s[2:3], exec
	s_cselect_b32 s13, s19, s17
	s_mov_b64 s[10:11], 0
